# dilated attention: splat(-reference) C operand kept permanently in v[114:129], the 8 register-pair copies per 64-key step between the two halves removed (on top of in-place PV in all paths)
# speedup vs baseline: 1.0065x; 1.0065x over previous
; #define LAS __attribute__((address_space(3)))
; template <int MODE> __device__ __forceinline__ void attn_unit(LAS unsigned char* lds, const AttnP& P, int b, int h, int qb) {
;     int tid_ = threadIdx.x; asm volatile("" : "+v"(tid_));
;     const int tid = tid_, lane = tid & 63, r32 = lane & 31, hi = lane >> 5, wid = __builtin_amdgcn_readfirstlane(tid >> 6);
;     const int tokbase = b * SEQ, q0 = qb * 256, q0w = q0 + wid * 32;
;     const int qcol = (MODE == 1) ? h * 64 : (MODE == 0) ? 768 + h * 64 : 1536 + h * 64;
;     const int kcol = (MODE == 1) ? 384 + h * 64 : (MODE == 0) ? 1152 + h * 64 : 1792 + h * 64;
;     const int vrow = (MODE == 1) ? h * 64 : (MODE == 0) ? 384 + h * 64 : 768 + h * 64;
;     const int t_hi = 4 * qb + 3; int t_lo = 0; if (MODE == 2) { t_lo = (q0 - 2048) >> 6; if (t_lo < 0) t_lo = 0; }
;     if (MODE == 0) {
;         LAS float* c2 = (LAS float*)(lds + L_C); LAS float* scan = (LAS float*)(lds + L_SCAN);
;         const int nel = 256 * (qb + 1); const float bf = P.b_f[h]; float v[8]; float run = 0.f;
; #pragma unroll
;         for (int e = 0; e < 8; ++e) { const int s = 8 * tid + e; float ls = 0.f;
;             if (s < nel) { const float x = P.FG[(size_t)(tokbase + s) * 8 + h] + bf;
;                 ls = fminf(x, 0.f) * LOG2E - __builtin_amdgcn_logf(1.0f + __builtin_amdgcn_exp2f(-fabsf(x) * LOG2E)); }
;             run += ls; v[e] = run; }
;         float inc = run;
; #pragma unroll
;         for (int o = 1; o < 64; o <<= 1) { const float t = __shfl_up(inc, o); if (lane >= o) inc += t; }
;         if (lane == 63) scan[wid] = inc;
;         __syncthreads();
;         float woff = 0.f;
; #pragma unroll
;         for (int w = 0; w < 8; ++w) { const float t = scan[w]; if (w < wid) woff += t; }
;         const float base = woff + inc - run;
;         if (8 * tid < nel) {
; #pragma unroll
;             for (int e = 0; e < 8; ++e) c2[8 * tid + e] = -(base + v[e]); }
;     }
;     bf16x8 qf[4];
;     { const bf16_t* qp = P.QKB + (size_t)(tokbase + q0w + r32) * NQK + qcol + 8 * hi;
; #pragma unroll
;       for (int c = 0; c < 4; ++c) qf[c] = *(const bf16x8*)(qp + 16 * c); }
;     const int lrow = tid >> 3, lch = tid & 7;
;     const bf16_t* kg = P.QKB + (size_t)(tokbase + lrow) * NQK + kcol + lch * 8;
;     const bf16_t* vg = P.VT + (size_t)(vrow + lrow) * MTOK + tokbase + lch * 8;
.LBB0_742:
	v_mov_b32_e32 v16, v240
	s_lshl_b32 s1, s2, 10
	s_and_b32 s1, s1, 0x1f000
	v_readfirstlane_b32 s0, v16
	s_add_i32 s16, s1, 0xfffe8000
	v_readlane_b32 s6, v251, 39
	s_ashr_i32 s0, s0, 1
	v_ashrrev_i32_e32 v12, 3, v16
	s_lshl_b32 s1, s6, 8
	s_and_b32 s33, s0, 0xffffffe0
	v_add_u32_e32 v6, s16, v12
	s_add_i32 s33, s33, s1
	s_addk_i32 s1, 0xf800
	v_ashrrev_i32_e32 v7, 31, v6
	v_readlane_b32 s4, v253, 46
	v_and_b32_e32 v2, 31, v16
	s_ashr_i32 s0, s1, 6
	s_add_i32 s1, s33, s16
	v_lshlrev_b64 v[6:7], 12, v[6:7]
	v_readlane_b32 s5, v253, 47
	v_lshlrev_b32_e32 v0, 4, v16
	v_or_b32_e32 v162, s1, v2
	v_lshl_add_u64 v[6:7], s[4:5], 0, v[6:7]
	v_and_b32_e32 v8, 0x70, v0
	v_mov_b32_e32 v9, v1
	v_readlane_b32 s1, v253, 48
	v_lshl_add_u64 v[164:165], v[6:7], 0, v[8:9]
	s_mov_b32 s36, s2
	v_add_u32_e32 v6, s1, v12
	v_ashrrev_i32_e32 v7, 31, v6
	v_readlane_b32 s2, v252, 29
	v_lshlrev_b64 v[6:7], 16, v[6:7]
	v_readlane_b32 s3, v252, 30
	s_max_i32 s0, s0, 0
	s_lshl_b32 s1, s0, 6
	v_lshl_add_u64 v[6:7], s[2:3], 0, v[6:7]
	v_lshl_add_u64 v[6:7], s[16:17], 1, v[6:7]
	s_lshl_b32 s16, s0, 18
	v_lshl_add_u64 v[166:167], v[6:7], 0, v[8:9]
	v_lshl_add_u64 v[6:7], v[164:165], 0, s[16:17]
	s_or_b32 s16, s1, 64
	s_lshl_b64 s[2:3], s[16:17], 12
	s_lshl_b32 s16, s0, 7
	v_lshl_add_u64 v[10:11], v[164:165], 0, s[2:3]
	global_load_dwordx4 v[130:133], v[6:7], off offset:3584
	global_load_dwordx4 v[134:137], v[10:11], off offset:3584
	v_lshl_add_u64 v[6:7], v[166:167], 0, s[16:17]
	global_load_dwordx4 v[138:141], v[6:7], off
	global_load_dwordx4 v[142:145], v[6:7], off offset:128
	v_ashrrev_i32_e32 v163, 31, v162
	v_bfe_u32 v3, v16, 5, 1
	v_lshlrev_b64 v[4:5], 12, v[162:163]
	v_lshl_add_u64 v[4:5], s[4:5], 0, v[4:5]
	v_lshlrev_b32_e32 v0, 4, v3
	v_lshl_add_u64 v[4:5], v[4:5], 0, v[0:1]
	global_load_dwordx4 v[146:149], v[4:5], off offset:3072
	global_load_dwordx4 v[150:153], v[4:5], off offset:3104
	global_load_dwordx4 v[154:157], v[4:5], off offset:3136
	global_load_dwordx4 v[158:161], v[4:5], off offset:3168
	s_movk_i32 s1, 0x90
	v_mul_lo_u32 v5, v12, s1
	v_and_b32_e32 v4, 63, v16
	v_lshlrev_b32_e32 v213, 2, v3
	v_add_u32_e32 v3, 0, v5
	v_lshlrev_b32_e32 v6, 7, v12
	v_lshl_add_u32 v4, v4, 6, 0
	v_sub_u32_e32 v19, v16, v213
	v_add_u32_e32 v215, v3, v8
	v_add_u32_e32 v214, 0x16000, v4
	v_sub_u32_e32 v4, v213, v16
	v_add3_u32 v3, v3, v6, v8
	v_and_b32_e32 v5, 15, v19
	v_add_u32_e32 v6, v215, v6
	v_and_b32_e32 v8, 15, v4
	v_cmp_eq_u32_e32 vcc, 0, v5
	v_and_b32_e32 v7, 3, v16
	v_add_u32_e32 v11, 13, v19
	v_cndmask_b32_e64 v4, 0, 1.0, vcc
	v_cmp_eq_u32_e32 vcc, 15, v8
	v_xor_b32_e32 v16, 8, v16
	v_and_b32_e32 v11, 15, v11
	v_cndmask_b32_e64 v5, 0, 1.0, vcc
	v_sub_u32_e32 v16, v16, v213
	v_and_b32_e32 v16, 15, v16
	v_cmp_eq_u32_e64 s[40:41], 0, v7
	v_cmp_eq_u32_e64 s[42:43], 1, v7
	v_cmp_eq_u32_e64 s[44:45], 2, v7
	v_cmp_eq_u32_e64 s[46:47], 3, v7
	v_cndmask_b32_e64 v17, 0, 1.0, s[40:41]
	v_add_f32_e32 v20, 1.0, v17
	v_add_f32_e32 v12, v17, v4
	v_cndmask_b32_e64 v18, 0, 1.0, s[42:43]
	v_add_f32_e32 v21, 1.0, v18
	v_add_f32_e32 v13, v18, v5
	s_lshl_b32 s50, s6, 1
	v_cndmask_b32_e64 v23, 0, 1.0, s[44:45]
	v_cndmask_b32_e64 v27, 0, 1.0, s[46:47]
	v_add_f32_e32 v22, 1.0, v23
	v_add_f32_e32 v28, 1.0, v27
	s_waitcnt vmcnt(7)
	ds_write_b128 v215, v[130:133]
	s_waitcnt vmcnt(6)
	ds_write_b128 v215, v[134:137] offset:9216
	s_waitcnt vmcnt(5)
	ds_write_b128 v3, v[138:141] offset:36864
	s_waitcnt vmcnt(4)
	ds_write_b128 v6, v[142:145] offset:36992
	v_add_u32_e32 v6, 14, v19
	v_and_b32_e32 v6, 15, v6
	v_cmp_eq_u32_e32 vcc, 0, v6
	s_lshr_b32 s51, s0, 1
	s_or_b32 s0, s50, 1
	v_cndmask_b32_e64 v6, 0, 1.0, vcc
	v_cmp_eq_u32_e32 vcc, 0, v11
	v_add_f32_e32 v8, v20, v4
	v_add_f32_e32 v9, v21, v5
	v_cndmask_b32_e64 v7, 0, 1.0, vcc
	v_cmp_eq_u32_e32 vcc, 0, v16
	v_add_f32_e32 v10, v22, v6
	v_add_f32_e32 v14, v23, v6
	v_cndmask_b32_e64 v16, 0, 1.0, vcc
	v_add_f32_e32 v24, v17, v16
	v_add_u32_e32 v17, 7, v19
	v_and_b32_e32 v17, 15, v17
	v_cmp_eq_u32_e32 vcc, 0, v17
	v_add_f32_e32 v11, v28, v7
	v_add_f32_e32 v20, v20, v16
	v_cndmask_b32_e64 v17, 0, 1.0, vcc
	v_add_f32_e32 v25, v18, v17
	v_add_u32_e32 v18, 6, v19
	v_and_b32_e32 v18, 15, v18
	v_add_u32_e32 v19, 5, v19
	v_cmp_eq_u32_e32 vcc, 0, v18
	v_and_b32_e32 v19, 15, v19
	v_add_f32_e32 v21, v21, v17
	v_cndmask_b32_e64 v18, 0, 1.0, vcc
	v_cmp_eq_u32_e32 vcc, 0, v19
	v_add_f32_e32 v22, v22, v18
	v_add_f32_e32 v26, v23, v18
	v_cndmask_b32_e64 v19, 0, 1.0, vcc
	v_add_f32_e32 v23, v28, v19
	s_cmp_gt_u32 s51, s0
	s_waitcnt lgkmcnt(0)
	s_barrier
	s_waitcnt vmcnt(3)
	s_waitcnt vmcnt(2)
	s_waitcnt vmcnt(1)
	s_waitcnt vmcnt(0)
	v_add_f32_e32 v15, v27, v7
	ds_write_b128 v214, v[8:11]
	ds_write_b128 v214, v[12:15] offset:4096
	ds_write_b128 v214, v[4:7] offset:8192
	v_add_f32_e32 v27, v27, v19
	ds_write_b128 v214, v[20:23] offset:16
	ds_write_b128 v214, v[24:27] offset:4112
	ds_write_b128 v214, v[16:19] offset:8208
	ds_write_b128 v214, v[8:11] offset:32
	ds_write_b128 v214, v[12:15] offset:4128
	ds_write_b128 v214, v[4:7] offset:8224
	ds_write_b128 v214, v[20:23] offset:48
	ds_write_b128 v214, v[24:27] offset:4144
	ds_write_b128 v214, v[16:19] offset:8240
	s_cbranch_scc1 .LBB0_794
	v_mov_b32_e32 v34, v1
	v_mov_b32_e32 v35, v1
	v_add_u32_e32 v216, 0x9000, v3
	v_mad_u32_u24 v217, v2, s1, v0
	v_or_b32_e32 v219, s33, v2
	v_mul_u32_u24_e32 v220, 0x110, v2
	v_mov_b32_e32 v36, v1
	v_mov_b32_e32 v37, v1
	v_mov_b32_e32 v38, v1
	v_mov_b32_e32 v39, v1
	v_mov_b32_e32 v40, v1
	v_mov_b32_e32 v41, v1
	v_mov_b32_e32 v42, v1
	v_mov_b32_e32 v43, v1
	v_mov_b32_e32 v44, v1
	v_mov_b32_e32 v45, v1
	v_mov_b32_e32 v46, v1
	v_mov_b32_e32 v47, v1
	v_mov_b32_e32 v48, v1
	v_mov_b32_e32 v49, v1
	v_mov_b32_e32 v114, v1
	v_mov_b32_e32 v115, v1
	v_mov_b32_e32 v116, v1
	v_mov_b32_e32 v117, v1
	v_mov_b32_e32 v118, v1
	v_mov_b32_e32 v119, v1
	v_mov_b32_e32 v120, v1
	v_mov_b32_e32 v121, v1
	v_mov_b32_e32 v122, v1
	v_mov_b32_e32 v123, v1
	v_mov_b32_e32 v124, v1
	v_mov_b32_e32 v125, v1
	v_mov_b32_e32 v126, v1
	v_mov_b32_e32 v127, v1
	v_mov_b32_e32 v128, v1
	v_mov_b32_e32 v129, v1
	v_mov_b64_e32 v[18:19], v[34:35]
	v_mov_b64_e32 v[2:3], v[34:35]
	v_add_u32_e32 v218, 0, v217
	s_or_b32 s52, s33, 31
	v_add3_u32 v221, 0, v220, v0
	s_mov_b64 s[0:1], -1
	v_mov_b32_e32 v223, 0
	s_mov_b32 s53, s51
	v_mov_b32_e32 v222, 0
	v_mov_b64_e32 v[20:21], v[36:37]
	v_mov_b64_e32 v[22:23], v[38:39]
	v_mov_b64_e32 v[24:25], v[40:41]
	v_mov_b64_e32 v[26:27], v[42:43]
	v_mov_b64_e32 v[28:29], v[44:45]
	v_mov_b64_e32 v[30:31], v[46:47]
	v_mov_b64_e32 v[32:33], v[48:49]
	v_mov_b64_e32 v[4:5], v[36:37]
	v_mov_b64_e32 v[6:7], v[38:39]
	v_mov_b64_e32 v[8:9], v[40:41]
	v_mov_b64_e32 v[10:11], v[42:43]
	v_mov_b64_e32 v[12:13], v[44:45]
	v_mov_b64_e32 v[14:15], v[46:47]
	v_mov_b64_e32 v[16:17], v[48:49]
	s_branch .LBB0_745

; template <int MODE> __device__ __forceinline__ void attn_unit(LAS unsigned char* lds, const AttnP& P, int b, int h, int qb) {
;     ...
;         bool act = (64 * t <= q0w + 31); if (MODE == 2) act = act && (q0w - 64 * t - 63 <= 2048);
;         if (pend) { pv(pvoff); pend = false; }
;         if (act) {
;             const LAS unsigned char* kb_ = lds + L_K + koff + fro;
;             const int dlt0 = (q0w + r32) - (64 * t + 4 * hi);
;             if (MODE == 1) {
;                 { f32x16 a0 = negm1, a1 = negm1;
; #pragma unroll
;                   for (int c = 0; c < 2; ++c) { const bf16x8 k0 = *(const LAS bf16x8*)(kb_ + c * 32), k1 = *(const LAS bf16x8*)(kb_ + 32 * ROWB + c * 32); a0 = MFMA32(k0, qf[c], a0); a1 = MFMA32(k1, qf[c], a1); }
;                   if (64 * t + 63 > q0w) { int dd = dlt0; asm volatile("" : "+v"(dd)); causal_mask(a0, a1, dd); }
;                   softmax_step<0, true>(a0, a1, m1, l1, oa0, oa1, first, wm0, 0, 0.f, &negm1);
;                   pa[0] = pack8(a0, 0); pa[1] = pack8(a0, 8); pa[2] = pack8(a1, 0); pa[3] = pack8(a1, 8); }
;                 { f32x16 b0 = negm2, b1 = negm2;
; #pragma unroll
;                   for (int c = 2; c < 4; ++c) { const bf16x8 k0 = *(const LAS bf16x8*)(kb_ + c * 32), k1 = *(const LAS bf16x8*)(kb_ + 32 * ROWB + c * 32); b0 = MFMA32(k0, qf[c], b0); b1 = MFMA32(k1, qf[c], b1); }
;                   if (64 * t + 63 > q0w) { int dd = dlt0; asm volatile("" : "+v"(dd)); causal_mask(b0, b1, dd); }
;                   softmax_step<0, true>(b0, b1, m2, l2, ob0, ob1, first, wm0, 0, 0.f, &negm2);
;                   pb[0] = pack8(b0, 0); pb[1] = pack8(b0, 8); pb[2] = pack8(b1, 0); pb[3] = pack8(b1, 8); }
;             } else {
;                 f32x16 p0 = negm1, p1 = negm1;
;                 if (MODE == 0) { const LAS float* cb = (const LAS float*)(lds + L_C) + 64 * t + 4 * hi;
; #pragma unroll
;                     for (int i = 0; i < 4; ++i) { const f32x4 c0 = *(const LAS f32x4*)(cb + 8 * i), c1 = *(const LAS f32x4*)(cb + 32 + 8 * i);
; #pragma unroll
;                         for (int j = 0; j < 4; ++j) { p0[4 * i + j] = c0[j]; p1[4 * i + j] = c1[j]; } } }
; #pragma unroll
;                 for (int c = 0; c < 4; ++c) { const bf16x8 k0 = *(const LAS bf16x8*)(kb_ + c * 32), k1 = *(const LAS bf16x8*)(kb_ + 32 * ROWB + c * 32); p0 = MFMA32(k0, qf[c], p0); p1 = MFMA32(k1, qf[c], p1); }
.LBB0_747:
	s_sub_i32 s2, s53, s51
	s_and_b32 s16, s2, 1
	s_cmp_gt_i32 s8, s52
	s_cselect_b64 s[4:5], -1, 0
	s_sub_i32 s3, s33, s8
	s_cmpk_gt_i32 s3, 0x83f
	s_cselect_b64 s[18:19], -1, 0
	s_or_b64 s[4:5], s[4:5], s[18:19]
	s_mul_i32 s2, s16, 0x4800
	s_and_b64 vcc, exec, s[4:5]
	s_cbranch_vccnz .LBB0_753
	v_add_u32_e32 v62, s2, v218
	ds_read_b128 v[50:53], v62
	ds_read_b128 v[54:57], v62 offset:32
	s_xor_b64 s[20:21], s[0:1], -1
	s_or_b32 s0, s8, 63
	s_sub_i32 s9, s33, s0
	s_waitcnt lgkmcnt(1)
	v_mfma_f32_32x32x16_bf16 v[66:81], v[50:53], v[146:149], v[114:129]
	ds_read_b128 v[50:53], v62 offset:4608
	ds_read_b128 v[58:61], v62 offset:4640
	s_or_b32 s3, s3, 31
	s_cmp_gt_i32 s9, -1
	s_cselect_b64 s[0:1], -1, 0
	s_cmpk_lt_i32 s3, 0x81
	s_cselect_b64 s[26:27], -1, 0
	s_and_b64 s[0:1], s[0:1], s[26:27]
	s_waitcnt lgkmcnt(1)
	v_mfma_f32_32x32x16_bf16 v[82:97], v[50:53], v[146:149], v[114:129]
	ds_read_b128 v[50:53], v62 offset:64
	s_cmpk_gt_i32 s9, 0x80
	s_cselect_b64 s[4:5], -1, 0
	s_cmpk_lt_i32 s3, 0x201
	s_cselect_b64 s[18:19], -1, 0
	s_and_b64 s[38:39], s[4:5], s[18:19]
	s_cmpk_gt_i32 s9, 0x200
	v_mfma_f32_32x32x16_bf16 v[66:81], v[54:57], v[150:153], v[66:81]
	s_cselect_b64 s[4:5], -1, 0
	s_cmpk_lt_i32 s3, 0x801
	s_cselect_b64 s[18:19], -1, 0
	s_and_b64 s[4:5], s[4:5], s[18:19]
	s_or_b64 s[0:1], s[0:1], s[38:39]
	s_or_b64 s[4:5], s[0:1], s[4:5]
	s_mov_b64 s[0:1], -1
	s_waitcnt lgkmcnt(1)
	v_mfma_f32_32x32x16_bf16 v[82:97], v[58:61], v[150:153], v[82:97]
	ds_read_b128 v[54:57], v62 offset:96
	ds_read_b128 v[58:61], v62 offset:4672
	ds_read_b128 v[62:65], v62 offset:4704
	s_andn2_b64 vcc, exec, s[4:5]
	s_waitcnt lgkmcnt(3)
	v_mfma_f32_32x32x16_bf16 v[66:81], v[50:53], v[154:157], v[66:81]
	s_waitcnt lgkmcnt(1)
	v_mfma_f32_32x32x16_bf16 v[82:97], v[58:61], v[154:157], v[82:97]
	s_waitcnt lgkmcnt(0)
	v_mfma_f32_32x32x16_bf16 v[82:97], v[62:65], v[158:161], v[82:97]
	v_mfma_f32_32x32x16_bf16 v[66:81], v[54:57], v[158:161], v[66:81]
	s_nop 10
	v_max_f32_e32 v225, v83, v83
	v_max_f32_e32 v226, v67, v67
	s_cbranch_vccz .LBB0_759
	v_max_f32_e32 v50, v226, v225
	v_max3_f32 v50, v66, v82, v50
	v_max3_f32 v50, v50, v68, v84
	v_max3_f32 v50, v50, v69, v85
	v_max3_f32 v50, v50, v70, v86
	v_max3_f32 v50, v50, v71, v87
	v_max3_f32 v50, v50, v72, v88
	v_max3_f32 v50, v50, v73, v89
	v_max3_f32 v50, v50, v74, v90
	v_max3_f32 v50, v50, v75, v91
	v_max3_f32 v50, v50, v76, v92
	v_max3_f32 v50, v50, v77, v93
	v_max3_f32 v50, v50, v78, v94
	v_max3_f32 v50, v50, v79, v95
	v_max3_f32 v50, v50, v80, v96
	v_max3_f32 v50, v50, v81, v97
	v_mov_b32_e32 v51, v50
	s_nop 1
	v_permlane32_swap_b32_e32 v50, v51
	v_max_f32_e32 v51, v51, v51
	v_max_f32_e32 v50, v50, v50
	v_max_f32_e32 v50, v50, v51
	s_and_b64 vcc, exec, s[20:21]
	s_cbranch_vccz .LBB0_754
	v_cmp_lt_f32_e32 vcc, s37, v50
	s_mov_b64 s[4:5], 0
	s_mov_b64 s[0:1], 0
	s_cbranch_vccz .LBB0_752
	v_max_f32_e32 v51, v50, v50
	v_max_f32_e32 v172, 0, v51
	s_mov_b64 s[0:1], -1

; template <int MODE> __device__ __forceinline__ void attn_unit(LAS unsigned char* lds, const AttnP& P, int b, int h, int qb) {
;     ...
;         bool act = (64 * t <= q0w + 31); if (MODE == 2) act = act && (q0w - 64 * t - 63 <= 2048);
;         if (pend) { pv(pvoff); pend = false; }
;         if (act) {
.LBB0_753:
	v_mov_b32_e32 v224, v223
	s_branch .LBB0_769

;     ...
;     if (first || __any(mx > SM_THR)) {
;         const float d = first ? mx : fmaxf(mx, 0.f), al = __builtin_amdgcn_exp2f(-d);
;         mref += d; l *= al;
; #pragma unroll
;         for (int r = 0; r < 16; ++r) { p0[r] -= d; p1[r] -= d; o0[r] *= al; o1[r] *= al; }
;         if (PRESUB) {
; #pragma unroll
;             for (int r = 0; r < 16; ++r) (*negm)[r] = -mref; }
;     }
.LBB0_756:
	s_andn2_b64 vcc, exec, s[0:1]
	v_mov_b32_e32 v227, v222
	v_mov_b32_e32 v224, v223
	s_cbranch_vccnz .LBB0_758
	v_exp_f32_e64 v50, -v172
	v_add_f32_e32 v224, v223, v172
	v_pk_add_f32 v[180:181], v[66:67], v[172:173] op_sel_hi:[1,0] neg_lo:[0,1] neg_hi:[0,1]
	v_pk_add_f32 v[176:177], v[82:83], v[172:173] op_sel_hi:[1,0] neg_lo:[0,1] neg_hi:[0,1]
	v_mul_f32_e32 v227, v222, v50
	v_pk_mul_f32 v[32:33], v[32:33], v[50:51] op_sel_hi:[1,0]
	v_pk_mul_f32 v[30:31], v[30:31], v[50:51] op_sel_hi:[1,0]
	v_pk_mul_f32 v[28:29], v[28:29], v[50:51] op_sel_hi:[1,0]
	v_pk_mul_f32 v[26:27], v[26:27], v[50:51] op_sel_hi:[1,0]
	v_pk_mul_f32 v[24:25], v[24:25], v[50:51] op_sel_hi:[1,0]
	v_pk_mul_f32 v[22:23], v[22:23], v[50:51] op_sel_hi:[1,0]
	v_pk_mul_f32 v[20:21], v[20:21], v[50:51] op_sel_hi:[1,0]
	v_pk_mul_f32 v[18:19], v[18:19], v[50:51] op_sel_hi:[1,0]
	v_pk_mul_f32 v[16:17], v[16:17], v[50:51] op_sel_hi:[1,0]
	v_pk_mul_f32 v[14:15], v[14:15], v[50:51] op_sel_hi:[1,0]
	v_pk_mul_f32 v[12:13], v[12:13], v[50:51] op_sel_hi:[1,0]
	v_pk_mul_f32 v[10:11], v[10:11], v[50:51] op_sel_hi:[1,0]
	v_pk_mul_f32 v[8:9], v[8:9], v[50:51] op_sel_hi:[1,0]
	v_pk_mul_f32 v[6:7], v[6:7], v[50:51] op_sel_hi:[1,0]
	v_pk_mul_f32 v[4:5], v[4:5], v[50:51] op_sel_hi:[1,0]
	v_pk_mul_f32 v[2:3], v[2:3], v[50:51] op_sel_hi:[1,0]
	v_xor_b32_e32 v50, 0x80000000, v224
	v_pk_add_f32 v[188:189], v[68:69], v[172:173] op_sel_hi:[1,0] neg_lo:[0,1] neg_hi:[0,1]
	v_pk_add_f32 v[184:185], v[84:85], v[172:173] op_sel_hi:[1,0] neg_lo:[0,1] neg_hi:[0,1]
	v_pk_add_f32 v[208:209], v[70:71], v[172:173] op_sel_hi:[1,0] neg_lo:[0,1] neg_hi:[0,1]
	v_pk_add_f32 v[204:205], v[86:87], v[172:173] op_sel_hi:[1,0] neg_lo:[0,1] neg_hi:[0,1]
	v_pk_add_f32 v[210:211], v[72:73], v[172:173] op_sel_hi:[1,0] neg_lo:[0,1] neg_hi:[0,1]
	v_pk_add_f32 v[206:207], v[88:89], v[172:173] op_sel_hi:[1,0] neg_lo:[0,1] neg_hi:[0,1]
	v_pk_add_f32 v[192:193], v[74:75], v[172:173] op_sel_hi:[1,0] neg_lo:[0,1] neg_hi:[0,1]
	v_pk_add_f32 v[190:191], v[90:91], v[172:173] op_sel_hi:[1,0] neg_lo:[0,1] neg_hi:[0,1]
	v_pk_add_f32 v[186:187], v[76:77], v[172:173] op_sel_hi:[1,0] neg_lo:[0,1] neg_hi:[0,1]
	v_pk_add_f32 v[182:183], v[92:93], v[172:173] op_sel_hi:[1,0] neg_lo:[0,1] neg_hi:[0,1]
	v_pk_add_f32 v[178:179], v[78:79], v[172:173] op_sel_hi:[1,0] neg_lo:[0,1] neg_hi:[0,1]
	v_pk_add_f32 v[174:175], v[94:95], v[172:173] op_sel_hi:[1,0] neg_lo:[0,1] neg_hi:[0,1]
	v_pk_add_f32 v[170:171], v[80:81], v[172:173] op_sel_hi:[1,0] neg_lo:[0,1] neg_hi:[0,1]
	v_pk_add_f32 v[168:169], v[96:97], v[172:173] op_sel_hi:[1,0] neg_lo:[0,1] neg_hi:[0,1]
	v_mov_b32_e32 v51, v50
	v_mov_b32_e32 v52, v50
	v_mov_b32_e32 v53, v50
	v_mov_b32_e32 v54, v50
	v_mov_b32_e32 v55, v50
	v_mov_b32_e32 v56, v50
	v_mov_b32_e32 v57, v50
	v_mov_b32_e32 v58, v50
	v_mov_b32_e32 v59, v50
	v_mov_b32_e32 v60, v50
	v_mov_b32_e32 v61, v50
	v_mov_b32_e32 v62, v50
	v_mov_b32_e32 v63, v50
	v_mov_b32_e32 v64, v50
	v_mov_b32_e32 v65, v50
	v_mov_b32_e32 v114, v50
	v_mov_b32_e32 v115, v50
	v_mov_b32_e32 v116, v50
	v_mov_b32_e32 v117, v50
	v_mov_b32_e32 v118, v50
	v_mov_b32_e32 v119, v50
	v_mov_b32_e32 v120, v50
	v_mov_b32_e32 v121, v50
	v_mov_b32_e32 v122, v50
	v_mov_b32_e32 v123, v50
	v_mov_b32_e32 v124, v50
	v_mov_b32_e32 v125, v50
	v_mov_b32_e32 v126, v50
	v_mov_b32_e32 v127, v50
	v_mov_b32_e32 v128, v50
	v_mov_b32_e32 v129, v50

;     ...
;     if (first || __any(mx > SM_THR)) {
;         const float d = first ? mx : fmaxf(mx, 0.f), al = __builtin_amdgcn_exp2f(-d);
;         mref += d; l *= al;
; #pragma unroll
;         for (int r = 0; r < 16; ++r) { p0[r] -= d; p1[r] -= d; o0[r] *= al; o1[r] *= al; }
;         if (PRESUB) {
; #pragma unroll
;             for (int r = 0; r < 16; ++r) (*negm)[r] = -mref; }
;     }
;     float s0 = 0.f, s1 = 0.f;
; #pragma unroll
;     for (int r = 0; r < 16; ++r) {
;         float e0 = __builtin_amdgcn_exp2f(p0[r]), e1 = __builtin_amdgcn_exp2f(p1[r]);
;         if (WMODE == 1) { e0 *= wa[r]; e1 *= wa[r]; }
;         if (WMODE == 4) { const int d0 = dlt0 - ((r & 3) + 8 * (r >> 2)), d1 = d0 - 32;
;             const float w0 = (((unsigned)d0 <= 128u) ? 1.f : 0.f) + ((((unsigned)d0 <= 512u) && ((d0 & 3) == 0)) ? 1.f : 0.f) + ((((unsigned)d0 <= 2048u) && ((d0 & 15) == 0)) ? 1.f : 0.f);
;             const float w1 = (((unsigned)d1 <= 128u) ? 1.f : 0.f) + ((((unsigned)d1 <= 512u) && ((d1 & 3) == 0)) ? 1.f : 0.f) + ((((unsigned)d1 <= 2048u) && ((d1 & 15) == 0)) ? 1.f : 0.f);
;             e0 *= w0; e1 *= w1; }
;         p0[r] = e0; p1[r] = e1; s0 += e0; s1 += e1; }
;     l += s0 + s1;
.LBB0_765:
	s_andn2_b64 vcc, exec, s[0:1]
	s_cbranch_vccnz .LBB0_767
	v_exp_f32_e64 v34, -v98
	v_add_f32_e32 v223, v223, v98
	v_pk_add_f32 v[66:67], v[66:67], v[98:99] op_sel_hi:[1,0] neg_lo:[0,1] neg_hi:[0,1]
	v_pk_add_f32 v[82:83], v[82:83], v[98:99] op_sel_hi:[1,0] neg_lo:[0,1] neg_hi:[0,1]
	v_mul_f32_e32 v222, v222, v34
	v_pk_mul_f32 v[32:33], v[32:33], v[34:35] op_sel_hi:[1,0]
	v_pk_mul_f32 v[30:31], v[30:31], v[34:35] op_sel_hi:[1,0]
	v_pk_mul_f32 v[28:29], v[28:29], v[34:35] op_sel_hi:[1,0]
	v_pk_mul_f32 v[26:27], v[26:27], v[34:35] op_sel_hi:[1,0]
	v_pk_mul_f32 v[24:25], v[24:25], v[34:35] op_sel_hi:[1,0]
	v_pk_mul_f32 v[22:23], v[22:23], v[34:35] op_sel_hi:[1,0]
	v_pk_mul_f32 v[20:21], v[20:21], v[34:35] op_sel_hi:[1,0]
	v_pk_mul_f32 v[18:19], v[18:19], v[34:35] op_sel_hi:[1,0]
	v_pk_mul_f32 v[16:17], v[16:17], v[34:35] op_sel_hi:[1,0]
	v_pk_mul_f32 v[14:15], v[14:15], v[34:35] op_sel_hi:[1,0]
	v_pk_mul_f32 v[12:13], v[12:13], v[34:35] op_sel_hi:[1,0]
	v_pk_mul_f32 v[10:11], v[10:11], v[34:35] op_sel_hi:[1,0]
	v_pk_mul_f32 v[8:9], v[8:9], v[34:35] op_sel_hi:[1,0]
	v_pk_mul_f32 v[6:7], v[6:7], v[34:35] op_sel_hi:[1,0]
	v_pk_mul_f32 v[4:5], v[4:5], v[34:35] op_sel_hi:[1,0]
	v_pk_mul_f32 v[2:3], v[2:3], v[34:35] op_sel_hi:[1,0]
	v_xor_b32_e32 v34, 0x80000000, v223
	v_pk_add_f32 v[68:69], v[68:69], v[98:99] op_sel_hi:[1,0] neg_lo:[0,1] neg_hi:[0,1]
	v_pk_add_f32 v[84:85], v[84:85], v[98:99] op_sel_hi:[1,0] neg_lo:[0,1] neg_hi:[0,1]
	v_pk_add_f32 v[70:71], v[70:71], v[98:99] op_sel_hi:[1,0] neg_lo:[0,1] neg_hi:[0,1]
	v_pk_add_f32 v[86:87], v[86:87], v[98:99] op_sel_hi:[1,0] neg_lo:[0,1] neg_hi:[0,1]
	v_pk_add_f32 v[72:73], v[72:73], v[98:99] op_sel_hi:[1,0] neg_lo:[0,1] neg_hi:[0,1]
	v_pk_add_f32 v[88:89], v[88:89], v[98:99] op_sel_hi:[1,0] neg_lo:[0,1] neg_hi:[0,1]
	v_pk_add_f32 v[74:75], v[74:75], v[98:99] op_sel_hi:[1,0] neg_lo:[0,1] neg_hi:[0,1]
	v_pk_add_f32 v[90:91], v[90:91], v[98:99] op_sel_hi:[1,0] neg_lo:[0,1] neg_hi:[0,1]
	v_pk_add_f32 v[76:77], v[76:77], v[98:99] op_sel_hi:[1,0] neg_lo:[0,1] neg_hi:[0,1]
	v_pk_add_f32 v[92:93], v[92:93], v[98:99] op_sel_hi:[1,0] neg_lo:[0,1] neg_hi:[0,1]
	v_pk_add_f32 v[78:79], v[78:79], v[98:99] op_sel_hi:[1,0] neg_lo:[0,1] neg_hi:[0,1]
	v_pk_add_f32 v[94:95], v[94:95], v[98:99] op_sel_hi:[1,0] neg_lo:[0,1] neg_hi:[0,1]
	v_pk_add_f32 v[80:81], v[80:81], v[98:99] op_sel_hi:[1,0] neg_lo:[0,1] neg_hi:[0,1]
	v_pk_add_f32 v[96:97], v[96:97], v[98:99] op_sel_hi:[1,0] neg_lo:[0,1] neg_hi:[0,1]
	v_mov_b32_e32 v35, v34
	v_mov_b32_e32 v36, v34
	v_mov_b32_e32 v37, v34
	v_mov_b32_e32 v38, v34
	v_mov_b32_e32 v39, v34
	v_mov_b32_e32 v40, v34
	v_mov_b32_e32 v41, v34
	v_mov_b32_e32 v42, v34
	v_mov_b32_e32 v43, v34
	v_mov_b32_e32 v44, v34
	v_mov_b32_e32 v45, v34
	v_mov_b32_e32 v46, v34
	v_mov_b32_e32 v47, v34
	v_mov_b32_e32 v48, v34
	v_mov_b32_e32 v49, v34
	v_mov_b32_e32 v114, v34
	v_mov_b32_e32 v115, v34
	v_mov_b32_e32 v116, v34
	v_mov_b32_e32 v117, v34
	v_mov_b32_e32 v118, v34
	v_mov_b32_e32 v119, v34
	v_mov_b32_e32 v120, v34
	v_mov_b32_e32 v121, v34
	v_mov_b32_e32 v122, v34
	v_mov_b32_e32 v123, v34
	v_mov_b32_e32 v124, v34
	v_mov_b32_e32 v125, v34
	v_mov_b32_e32 v126, v34
	v_mov_b32_e32 v127, v34
	v_mov_b32_e32 v128, v34
	v_mov_b32_e32 v129, v34
.LBB0_767:
	v_exp_f32_e32 v99, v66
	v_exp_f32_e32 v98, v82
	v_exp_f32_e32 v67, v67
	v_exp_f32_e32 v66, v83
	v_exp_f32_e32 v83, v68
	v_exp_f32_e32 v82, v84
	v_exp_f32_e32 v69, v69
	v_exp_f32_e32 v68, v85
	s_waitcnt lgkmcnt(3)
	v_pk_fma_f32 v[84:85], v[62:63], v[98:99], 0 op_sel_hi:[0,1,0]
	v_pk_mul_f32 v[172:173], v[62:63], v[98:99] op_sel_hi:[0,1]
	v_pk_mul_f32 v[176:177], v[62:63], v[66:67] op_sel:[1,0]
	v_pk_fma_f32 v[62:63], v[62:63], v[66:67], v[84:85] op_sel:[1,0,0]
	v_pk_mul_f32 v[180:181], v[64:65], v[82:83] op_sel_hi:[0,1]
	v_pk_fma_f32 v[62:63], v[64:65], v[82:83], v[62:63] op_sel_hi:[0,1,1]
	v_exp_f32_e32 v67, v70
	v_exp_f32_e32 v66, v86
	v_mov_b32_e32 v64, v65
	v_pk_mul_f32 v[184:185], v[64:65], v[68:69] op_sel_hi:[0,1]
	v_pk_fma_f32 v[62:63], v[64:65], v[68:69], v[62:63] op_sel_hi:[0,1,1]
	v_exp_f32_e32 v65, v71
	v_exp_f32_e32 v64, v87
	v_exp_f32_e32 v69, v72
	v_exp_f32_e32 v68, v88
	v_exp_f32_e32 v71, v73
	v_exp_f32_e32 v70, v89
	v_exp_f32_e32 v73, v74
	v_exp_f32_e32 v72, v90
	s_waitcnt lgkmcnt(2)
	v_pk_fma_f32 v[62:63], v[58:59], v[66:67], v[62:63] op_sel_hi:[0,1,1]
	v_pk_mul_f32 v[188:189], v[58:59], v[66:67] op_sel_hi:[0,1]
	v_exp_f32_e32 v75, v75
	v_exp_f32_e32 v74, v91
	v_pk_mul_f32 v[204:205], v[58:59], v[64:65] op_sel:[1,0]
	v_pk_fma_f32 v[58:59], v[58:59], v[64:65], v[62:63] op_sel:[1,0,0]
	v_exp_f32_e32 v83, v76
	v_exp_f32_e32 v82, v92
	v_pk_mul_f32 v[208:209], v[60:61], v[68:69] op_sel_hi:[0,1]
	v_pk_fma_f32 v[58:59], v[60:61], v[68:69], v[58:59] op_sel_hi:[0,1,1]
	v_mov_b32_e32 v60, v61
	v_exp_f32_e32 v77, v77
	v_exp_f32_e32 v76, v93
	v_pk_fma_f32 v[58:59], v[60:61], v[70:71], v[58:59] op_sel_hi:[0,1,1]
	v_exp_f32_e32 v85, v78
	v_exp_f32_e32 v84, v94
	s_waitcnt lgkmcnt(1)
	v_pk_fma_f32 v[58:59], v[54:55], v[72:73], v[58:59] op_sel_hi:[0,1,1]
	v_exp_f32_e32 v79, v79
	v_exp_f32_e32 v78, v95
	v_pk_mul_f32 v[210:211], v[54:55], v[72:73] op_sel_hi:[0,1]
	v_pk_mul_f32 v[190:191], v[54:55], v[74:75] op_sel:[1,0]
	v_pk_fma_f32 v[54:55], v[54:55], v[74:75], v[58:59] op_sel:[1,0,0]
	v_exp_f32_e32 v87, v80
	v_exp_f32_e32 v86, v96
	v_pk_mul_f32 v[192:193], v[56:57], v[82:83] op_sel_hi:[0,1]
	v_pk_fma_f32 v[54:55], v[56:57], v[82:83], v[54:55] op_sel_hi:[0,1,1]
	v_mov_b32_e32 v56, v57
	v_exp_f32_e32 v81, v81
	v_exp_f32_e32 v80, v97
	v_pk_fma_f32 v[54:55], v[56:57], v[76:77], v[54:55] op_sel_hi:[0,1,1]
	s_waitcnt lgkmcnt(0)
	v_pk_fma_f32 v[54:55], v[50:51], v[84:85], v[54:55] op_sel_hi:[0,1,1]
	v_pk_mul_f32 v[186:187], v[50:51], v[84:85] op_sel_hi:[0,1]
	v_pk_mul_f32 v[174:175], v[50:51], v[78:79] op_sel:[1,0]
	v_pk_fma_f32 v[50:51], v[50:51], v[78:79], v[54:55] op_sel:[1,0,0]
	v_pk_mul_f32 v[178:179], v[52:53], v[86:87] op_sel_hi:[0,1]
	v_pk_fma_f32 v[50:51], v[52:53], v[86:87], v[50:51] op_sel_hi:[0,1,1]
	v_mov_b32_e32 v52, v53
	v_pk_fma_f32 v[50:51], v[52:53], v[80:81], v[50:51] op_sel_hi:[0,1,1]
	v_pk_mul_f32 v[206:207], v[60:61], v[70:71] op_sel_hi:[0,1]
	v_pk_mul_f32 v[182:183], v[56:57], v[76:77] op_sel_hi:[0,1]
	v_pk_mul_f32 v[168:169], v[52:53], v[80:81] op_sel_hi:[0,1]
	v_add_f32_e32 v170, v50, v51
	v_mov_b32_e32 v224, v223
	v_mov_b32_e32 v227, v222

; template <int MODE> __device__ __forceinline__ void attn_unit(LAS unsigned char* lds, const AttnP& P, int b, int h, int qb) {
;     ...
;         bool act = (64 * t <= q0w + 31); if (MODE == 2) act = act && (q0w - 64 * t - 63 <= 2048);
;         if (pend) { pv(pvoff); pend = false; }
;         if (act) {
;             const LAS unsigned char* kb_ = lds + L_K + koff + fro;
;             const int dlt0 = (q0w + r32) - (64 * t + 4 * hi);
;             if (MODE == 1) {
;                 { f32x16 a0 = negm1, a1 = negm1;
; #pragma unroll
;                   for (int c = 0; c < 2; ++c) { const bf16x8 k0 = *(const LAS bf16x8*)(kb_ + c * 32), k1 = *(const LAS bf16x8*)(kb_ + 32 * ROWB + c * 32); a0 = MFMA32(k0, qf[c], a0); a1 = MFMA32(k1, qf[c], a1); }
;                   if (64 * t + 63 > q0w) { int dd = dlt0; asm volatile("" : "+v"(dd)); causal_mask(a0, a1, dd); }
;                   softmax_step<0, true>(a0, a1, m1, l1, oa0, oa1, first, wm0, 0, 0.f, &negm1);
;                   pa[0] = pack8(a0, 0); pa[1] = pack8(a0, 8); pa[2] = pack8(a1, 0); pa[3] = pack8(a1, 8); }
;                 { f32x16 b0 = negm2, b1 = negm2;
; #pragma unroll
;                   for (int c = 2; c < 4; ++c) { const bf16x8 k0 = *(const LAS bf16x8*)(kb_ + c * 32), k1 = *(const LAS bf16x8*)(kb_ + 32 * ROWB + c * 32); b0 = MFMA32(k0, qf[c], b0); b1 = MFMA32(k1, qf[c], b1); }
;                   if (64 * t + 63 > q0w) { int dd = dlt0; asm volatile("" : "+v"(dd)); causal_mask(b0, b1, dd); }
;                   softmax_step<0, true>(b0, b1, m2, l2, ob0, ob1, first, wm0, 0, 0.f, &negm2);
;                   pb[0] = pack8(b0, 0); pb[1] = pack8(b0, 8); pb[2] = pack8(b1, 0); pb[3] = pack8(b1, 8); }
;             } else {
;                 f32x16 p0 = negm1, p1 = negm1;
;                 if (MODE == 0) { const LAS float* cb = (const LAS float*)(lds + L_C) + 64 * t + 4 * hi;
; #pragma unroll
;                     for (int i = 0; i < 4; ++i) { const f32x4 c0 = *(const LAS f32x4*)(cb + 8 * i), c1 = *(const LAS f32x4*)(cb + 32 + 8 * i);
; #pragma unroll
;                         for (int j = 0; j < 4; ++j) { p0[4 * i + j] = c0[j]; p1[4 * i + j] = c1[j]; } } }
; #pragma unroll
;                 for (int c = 0; c < 4; ++c) { const bf16x8 k0 = *(const LAS bf16x8*)(kb_ + c * 32), k1 = *(const LAS bf16x8*)(kb_ + 32 * ROWB + c * 32); p0 = MFMA32(k0, qf[c], p0); p1 = MFMA32(k1, qf[c], p1); }
.LBB0_769:
	s_or_b32 s3, s8, 64
	s_cmp_gt_i32 s3, s52
	s_cselect_b64 s[18:19], -1, 0
	s_sub_i32 s4, s33, s3
	s_cmpk_gt_i32 s4, 0x83f
	s_cselect_b64 s[20:21], -1, 0
	s_or_b64 s[18:19], s[18:19], s[20:21]
	s_and_b64 vcc, exec, s[18:19]
	s_cbranch_vccnz .LBB0_775
	s_add_i32 s2, s2, 0
	v_add_u32_e32 v46, s2, v217
	ds_read_b128 v[34:37], v46 offset:9216
	ds_read_b128 v[38:41], v46 offset:9248
	s_xor_b64 s[20:21], s[0:1], -1
	s_or_b32 s0, s8, 0x7f
	s_sub_i32 s34, s33, s0
	s_waitcnt lgkmcnt(1)
	v_mfma_f32_32x32x16_bf16 v[66:81], v[34:37], v[146:149], v[114:129]
	ds_read_b128 v[34:37], v46 offset:13824
	ds_read_b128 v[42:45], v46 offset:13856
	s_or_b32 s35, s4, 31
	s_cmp_gt_i32 s34, -1
	s_cselect_b64 s[0:1], -1, 0
	s_cmpk_lt_i32 s35, 0x81
	s_cselect_b64 s[8:9], -1, 0
	s_and_b64 s[0:1], s[0:1], s[8:9]
	s_waitcnt lgkmcnt(1)
	v_mfma_f32_32x32x16_bf16 v[82:97], v[34:37], v[146:149], v[114:129]
	ds_read_b128 v[34:37], v46 offset:9280
	s_cmpk_gt_i32 s34, 0x80
	s_cselect_b64 s[4:5], -1, 0
	s_cmpk_lt_i32 s35, 0x201
	s_cselect_b64 s[18:19], -1, 0
	s_and_b64 s[26:27], s[4:5], s[18:19]
	s_cmpk_gt_i32 s34, 0x200
	v_mfma_f32_32x32x16_bf16 v[66:81], v[38:41], v[150:153], v[66:81]
	s_cselect_b64 s[4:5], -1, 0
	s_cmpk_lt_i32 s35, 0x801
	s_cselect_b64 s[18:19], -1, 0
	s_and_b64 s[4:5], s[4:5], s[18:19]
	s_or_b64 s[0:1], s[0:1], s[26:27]
	s_or_b64 s[4:5], s[0:1], s[4:5]
	s_mov_b64 s[0:1], -1
	s_waitcnt lgkmcnt(1)
	v_mfma_f32_32x32x16_bf16 v[82:97], v[42:45], v[150:153], v[82:97]
	ds_read_b128 v[38:41], v46 offset:9312
	ds_read_b128 v[42:45], v46 offset:13888
	ds_read_b128 v[46:49], v46 offset:13920
	s_andn2_b64 vcc, exec, s[4:5]
	s_waitcnt lgkmcnt(3)
	v_mfma_f32_32x32x16_bf16 v[66:81], v[34:37], v[154:157], v[66:81]
	s_waitcnt lgkmcnt(1)
	v_mfma_f32_32x32x16_bf16 v[82:97], v[42:45], v[154:157], v[82:97]
	s_waitcnt lgkmcnt(0)
	v_mfma_f32_32x32x16_bf16 v[82:97], v[46:49], v[158:161], v[82:97]
	v_mfma_f32_32x32x16_bf16 v[66:81], v[38:41], v[158:161], v[66:81]
	s_nop 10
	v_max_f32_e32 v225, v83, v83
	v_max_f32_e32 v226, v67, v67
	s_cbranch_vccz .LBB0_782
	v_max_f32_e32 v34, v226, v225
	v_max3_f32 v34, v66, v82, v34
	v_max3_f32 v34, v34, v68, v84
	v_max3_f32 v34, v34, v69, v85
	v_max3_f32 v34, v34, v70, v86
	v_max3_f32 v34, v34, v71, v87
	v_max3_f32 v34, v34, v72, v88
	v_max3_f32 v34, v34, v73, v89
	v_max3_f32 v34, v34, v74, v90
	v_max3_f32 v34, v34, v75, v91
	v_max3_f32 v34, v34, v76, v92
	v_max3_f32 v34, v34, v77, v93
	v_max3_f32 v34, v34, v78, v94
	v_max3_f32 v34, v34, v79, v95
	v_max3_f32 v34, v34, v80, v96
	v_max3_f32 v34, v34, v81, v97
	v_mov_b32_e32 v35, v34
	s_nop 1
	v_permlane32_swap_b32_e32 v34, v35
	v_max_f32_e32 v35, v35, v35
	v_max_f32_e32 v34, v34, v34
	v_max_f32_e32 v34, v34, v35
	s_and_b64 vcc, exec, s[20:21]
	s_cbranch_vccz .LBB0_777
	v_cmp_lt_f32_e32 vcc, s37, v34
	s_mov_b64 s[4:5], 0
	s_mov_b64 s[0:1], 0
	s_cbranch_vccz .LBB0_774
	v_max_f32_e32 v35, v34, v34
	v_max_f32_e32 v172, 0, v35
	s_mov_b64 s[0:1], -1

; #define ATT_GLOAD(dst, ptr) asm volatile("global_load_dwordx4 %0, %1, off" : "+v"(dst) : "v"(ptr) : "memory")
; template <int MODE> __device__ __forceinline__ void attn_unit(LAS unsigned char* lds, const AttnP& P, int b, int h, int qb) {
;     ...
;     for (int T = T_lo; T <= T_hi; ++T) {
;         const int buf = (T - T_lo) & 1; const bool more = T < T_hi;
;         if (more) { const bf16_t* kp = kg + (size_t)((T + 1) * 128) * NQK; const bf16_t* vp = vg + (T + 1) * 128;
;             ATT_GLOAD(ka, kp); ATT_GLOAD(kb2, kp + (size_t)64 * NQK); ATT_GLOAD(va, vp); ATT_GLOAD(vb2, vp + 64); }
;         compute(2 * T, buf * KSTEP, buf * VSTEP);
;         compute(2 * T + 1, buf * KSTEP + TILEB, buf * VSTEP + 128);
;         if (more) { const unsigned kw = ldsKw + (unsigned)((buf ^ 1) * KSTEP), vw = ldsVw + (unsigned)((buf ^ 1) * VSTEP);
;             asm volatile("s_waitcnt vmcnt(0)\n\tds_write_b128 %0, %1\n\tds_write_b128 %0, %2 offset:9216\n\tds_write_b128 %3, %4\n\tds_write_b128 %3, %5 offset:128"
;                          :: "v"(kw), "v"(ka), "v"(kb2), "v"(vw), "v"(va), "v"(vb2) : "memory"); }
;         asm volatile("s_waitcnt lgkmcnt(0)\n\ts_barrier" ::: "memory");
;     }
.LBB0_775:
	v_mov_b32_e32 v223, v224
	s_andn2_b64 vcc, exec, s[48:49]
	s_cbranch_vccnz .LBB0_744
	s_branch .LBB0_792

;     ...
;     if (first || __any(mx > SM_THR)) {
;         const float d = first ? mx : fmaxf(mx, 0.f), al = __builtin_amdgcn_exp2f(-d);
;         mref += d; l *= al;
; #pragma unroll
;         for (int r = 0; r < 16; ++r) { p0[r] -= d; p1[r] -= d; o0[r] *= al; o1[r] *= al; }
;         if (PRESUB) {
; #pragma unroll
;             for (int r = 0; r < 16; ++r) (*negm)[r] = -mref; }
;     }
.LBB0_779:
	s_andn2_b64 vcc, exec, s[0:1]
	v_mov_b32_e32 v227, v222
	v_mov_b32_e32 v223, v224
	s_cbranch_vccnz .LBB0_781
	v_exp_f32_e64 v34, -v172
	v_add_f32_e32 v223, v224, v172
	v_pk_add_f32 v[180:181], v[66:67], v[172:173] op_sel_hi:[1,0] neg_lo:[0,1] neg_hi:[0,1]
	v_pk_add_f32 v[176:177], v[82:83], v[172:173] op_sel_hi:[1,0] neg_lo:[0,1] neg_hi:[0,1]
	v_mul_f32_e32 v227, v222, v34
	v_pk_mul_f32 v[32:33], v[32:33], v[34:35] op_sel_hi:[1,0]
	v_pk_mul_f32 v[30:31], v[30:31], v[34:35] op_sel_hi:[1,0]
	v_pk_mul_f32 v[28:29], v[28:29], v[34:35] op_sel_hi:[1,0]
	v_pk_mul_f32 v[26:27], v[26:27], v[34:35] op_sel_hi:[1,0]
	v_pk_mul_f32 v[24:25], v[24:25], v[34:35] op_sel_hi:[1,0]
	v_pk_mul_f32 v[22:23], v[22:23], v[34:35] op_sel_hi:[1,0]
	v_pk_mul_f32 v[20:21], v[20:21], v[34:35] op_sel_hi:[1,0]
	v_pk_mul_f32 v[18:19], v[18:19], v[34:35] op_sel_hi:[1,0]
	v_pk_mul_f32 v[16:17], v[16:17], v[34:35] op_sel_hi:[1,0]
	v_pk_mul_f32 v[14:15], v[14:15], v[34:35] op_sel_hi:[1,0]
	v_pk_mul_f32 v[12:13], v[12:13], v[34:35] op_sel_hi:[1,0]
	v_pk_mul_f32 v[10:11], v[10:11], v[34:35] op_sel_hi:[1,0]
	v_pk_mul_f32 v[8:9], v[8:9], v[34:35] op_sel_hi:[1,0]
	v_pk_mul_f32 v[6:7], v[6:7], v[34:35] op_sel_hi:[1,0]
	v_pk_mul_f32 v[4:5], v[4:5], v[34:35] op_sel_hi:[1,0]
	v_pk_mul_f32 v[2:3], v[2:3], v[34:35] op_sel_hi:[1,0]
	v_xor_b32_e32 v34, 0x80000000, v223
	v_pk_add_f32 v[188:189], v[68:69], v[172:173] op_sel_hi:[1,0] neg_lo:[0,1] neg_hi:[0,1]
	v_pk_add_f32 v[184:185], v[84:85], v[172:173] op_sel_hi:[1,0] neg_lo:[0,1] neg_hi:[0,1]
	v_pk_add_f32 v[208:209], v[70:71], v[172:173] op_sel_hi:[1,0] neg_lo:[0,1] neg_hi:[0,1]
	v_pk_add_f32 v[204:205], v[86:87], v[172:173] op_sel_hi:[1,0] neg_lo:[0,1] neg_hi:[0,1]
	v_pk_add_f32 v[210:211], v[72:73], v[172:173] op_sel_hi:[1,0] neg_lo:[0,1] neg_hi:[0,1]
	v_pk_add_f32 v[206:207], v[88:89], v[172:173] op_sel_hi:[1,0] neg_lo:[0,1] neg_hi:[0,1]
	v_pk_add_f32 v[192:193], v[74:75], v[172:173] op_sel_hi:[1,0] neg_lo:[0,1] neg_hi:[0,1]
	v_pk_add_f32 v[190:191], v[90:91], v[172:173] op_sel_hi:[1,0] neg_lo:[0,1] neg_hi:[0,1]
	v_pk_add_f32 v[186:187], v[76:77], v[172:173] op_sel_hi:[1,0] neg_lo:[0,1] neg_hi:[0,1]
	v_pk_add_f32 v[182:183], v[92:93], v[172:173] op_sel_hi:[1,0] neg_lo:[0,1] neg_hi:[0,1]
	v_pk_add_f32 v[178:179], v[78:79], v[172:173] op_sel_hi:[1,0] neg_lo:[0,1] neg_hi:[0,1]
	v_pk_add_f32 v[174:175], v[94:95], v[172:173] op_sel_hi:[1,0] neg_lo:[0,1] neg_hi:[0,1]
	v_pk_add_f32 v[170:171], v[80:81], v[172:173] op_sel_hi:[1,0] neg_lo:[0,1] neg_hi:[0,1]
	v_pk_add_f32 v[168:169], v[96:97], v[172:173] op_sel_hi:[1,0] neg_lo:[0,1] neg_hi:[0,1]
	v_mov_b32_e32 v35, v34
	v_mov_b32_e32 v36, v34
	v_mov_b32_e32 v37, v34
	v_mov_b32_e32 v38, v34
	v_mov_b32_e32 v39, v34
	v_mov_b32_e32 v40, v34
	v_mov_b32_e32 v41, v34
	v_mov_b32_e32 v42, v34
	v_mov_b32_e32 v43, v34
	v_mov_b32_e32 v44, v34
	v_mov_b32_e32 v45, v34
	v_mov_b32_e32 v46, v34
	v_mov_b32_e32 v47, v34
	v_mov_b32_e32 v48, v34
	v_mov_b32_e32 v49, v34
	v_mov_b32_e32 v114, v34
	v_mov_b32_e32 v115, v34
	v_mov_b32_e32 v116, v34
	v_mov_b32_e32 v117, v34
	v_mov_b32_e32 v118, v34
	v_mov_b32_e32 v119, v34
	v_mov_b32_e32 v120, v34
	v_mov_b32_e32 v121, v34
	v_mov_b32_e32 v122, v34
	v_mov_b32_e32 v123, v34
	v_mov_b32_e32 v124, v34
	v_mov_b32_e32 v125, v34
	v_mov_b32_e32 v126, v34
	v_mov_b32_e32 v127, v34
	v_mov_b32_e32 v128, v34
	v_mov_b32_e32 v129, v34

;     ...
;     if (first || __any(mx > SM_THR)) {
;         const float d = first ? mx : fmaxf(mx, 0.f), al = __builtin_amdgcn_exp2f(-d);
;         mref += d; l *= al;
; #pragma unroll
;         for (int r = 0; r < 16; ++r) { p0[r] -= d; p1[r] -= d; o0[r] *= al; o1[r] *= al; }
;         if (PRESUB) {
; #pragma unroll
;             for (int r = 0; r < 16; ++r) (*negm)[r] = -mref; }
;     }
;     float s0 = 0.f, s1 = 0.f;
; #pragma unroll
;     for (int r = 0; r < 16; ++r) {
;         float e0 = __builtin_amdgcn_exp2f(p0[r]), e1 = __builtin_amdgcn_exp2f(p1[r]);
;         if (WMODE == 1) { e0 *= wa[r]; e1 *= wa[r]; }
;         if (WMODE == 4) { const int d0 = dlt0 - ((r & 3) + 8 * (r >> 2)), d1 = d0 - 32;
;             const float w0 = (((unsigned)d0 <= 128u) ? 1.f : 0.f) + ((((unsigned)d0 <= 512u) && ((d0 & 3) == 0)) ? 1.f : 0.f) + ((((unsigned)d0 <= 2048u) && ((d0 & 15) == 0)) ? 1.f : 0.f);
;             const float w1 = (((unsigned)d1 <= 128u) ? 1.f : 0.f) + ((((unsigned)d1 <= 512u) && ((d1 & 3) == 0)) ? 1.f : 0.f) + ((((unsigned)d1 <= 2048u) && ((d1 & 15) == 0)) ? 1.f : 0.f);
;             e0 *= w0; e1 *= w1; }
;         p0[r] = e0; p1[r] = e1; s0 += e0; s1 += e1; }
;     l += s0 + s1;
.LBB0_788:
	s_andn2_b64 vcc, exec, s[0:1]
	s_cbranch_vccnz .LBB0_790
	v_exp_f32_e64 v50, -v98
	v_add_f32_e32 v224, v224, v98
	v_pk_add_f32 v[66:67], v[66:67], v[98:99] op_sel_hi:[1,0] neg_lo:[0,1] neg_hi:[0,1]
	v_pk_add_f32 v[82:83], v[82:83], v[98:99] op_sel_hi:[1,0] neg_lo:[0,1] neg_hi:[0,1]
	v_mul_f32_e32 v222, v222, v50
	v_pk_mul_f32 v[32:33], v[32:33], v[50:51] op_sel_hi:[1,0]
	v_pk_mul_f32 v[30:31], v[30:31], v[50:51] op_sel_hi:[1,0]
	v_pk_mul_f32 v[28:29], v[28:29], v[50:51] op_sel_hi:[1,0]
	v_pk_mul_f32 v[26:27], v[26:27], v[50:51] op_sel_hi:[1,0]
	v_pk_mul_f32 v[24:25], v[24:25], v[50:51] op_sel_hi:[1,0]
	v_pk_mul_f32 v[22:23], v[22:23], v[50:51] op_sel_hi:[1,0]
	v_pk_mul_f32 v[20:21], v[20:21], v[50:51] op_sel_hi:[1,0]
	v_pk_mul_f32 v[18:19], v[18:19], v[50:51] op_sel_hi:[1,0]
	v_pk_mul_f32 v[16:17], v[16:17], v[50:51] op_sel_hi:[1,0]
	v_pk_mul_f32 v[14:15], v[14:15], v[50:51] op_sel_hi:[1,0]
	v_pk_mul_f32 v[12:13], v[12:13], v[50:51] op_sel_hi:[1,0]
	v_pk_mul_f32 v[10:11], v[10:11], v[50:51] op_sel_hi:[1,0]
	v_pk_mul_f32 v[8:9], v[8:9], v[50:51] op_sel_hi:[1,0]
	v_pk_mul_f32 v[6:7], v[6:7], v[50:51] op_sel_hi:[1,0]
	v_pk_mul_f32 v[4:5], v[4:5], v[50:51] op_sel_hi:[1,0]
	v_pk_mul_f32 v[2:3], v[2:3], v[50:51] op_sel_hi:[1,0]
	v_xor_b32_e32 v50, 0x80000000, v224
	v_pk_add_f32 v[68:69], v[68:69], v[98:99] op_sel_hi:[1,0] neg_lo:[0,1] neg_hi:[0,1]
	v_pk_add_f32 v[84:85], v[84:85], v[98:99] op_sel_hi:[1,0] neg_lo:[0,1] neg_hi:[0,1]
	v_pk_add_f32 v[70:71], v[70:71], v[98:99] op_sel_hi:[1,0] neg_lo:[0,1] neg_hi:[0,1]
	v_pk_add_f32 v[86:87], v[86:87], v[98:99] op_sel_hi:[1,0] neg_lo:[0,1] neg_hi:[0,1]
	v_pk_add_f32 v[72:73], v[72:73], v[98:99] op_sel_hi:[1,0] neg_lo:[0,1] neg_hi:[0,1]
	v_pk_add_f32 v[88:89], v[88:89], v[98:99] op_sel_hi:[1,0] neg_lo:[0,1] neg_hi:[0,1]
	v_pk_add_f32 v[74:75], v[74:75], v[98:99] op_sel_hi:[1,0] neg_lo:[0,1] neg_hi:[0,1]
	v_pk_add_f32 v[90:91], v[90:91], v[98:99] op_sel_hi:[1,0] neg_lo:[0,1] neg_hi:[0,1]
	v_pk_add_f32 v[76:77], v[76:77], v[98:99] op_sel_hi:[1,0] neg_lo:[0,1] neg_hi:[0,1]
	v_pk_add_f32 v[92:93], v[92:93], v[98:99] op_sel_hi:[1,0] neg_lo:[0,1] neg_hi:[0,1]
	v_pk_add_f32 v[78:79], v[78:79], v[98:99] op_sel_hi:[1,0] neg_lo:[0,1] neg_hi:[0,1]
	v_pk_add_f32 v[94:95], v[94:95], v[98:99] op_sel_hi:[1,0] neg_lo:[0,1] neg_hi:[0,1]
	v_pk_add_f32 v[80:81], v[80:81], v[98:99] op_sel_hi:[1,0] neg_lo:[0,1] neg_hi:[0,1]
	v_pk_add_f32 v[96:97], v[96:97], v[98:99] op_sel_hi:[1,0] neg_lo:[0,1] neg_hi:[0,1]
	v_mov_b32_e32 v51, v50
	v_mov_b32_e32 v52, v50
	v_mov_b32_e32 v53, v50
	v_mov_b32_e32 v54, v50
	v_mov_b32_e32 v55, v50
	v_mov_b32_e32 v56, v50
	v_mov_b32_e32 v57, v50
	v_mov_b32_e32 v58, v50
	v_mov_b32_e32 v59, v50
	v_mov_b32_e32 v60, v50
	v_mov_b32_e32 v61, v50
	v_mov_b32_e32 v62, v50
	v_mov_b32_e32 v63, v50
	v_mov_b32_e32 v64, v50
	v_mov_b32_e32 v65, v50
	v_mov_b32_e32 v114, v50
	v_mov_b32_e32 v115, v50
	v_mov_b32_e32 v116, v50
	v_mov_b32_e32 v117, v50
	v_mov_b32_e32 v118, v50
	v_mov_b32_e32 v119, v50
	v_mov_b32_e32 v120, v50
	v_mov_b32_e32 v121, v50
	v_mov_b32_e32 v122, v50
	v_mov_b32_e32 v123, v50
	v_mov_b32_e32 v124, v50
	v_mov_b32_e32 v125, v50
	v_mov_b32_e32 v126, v50
	v_mov_b32_e32 v127, v50
	v_mov_b32_e32 v128, v50
	v_mov_b32_e32 v129, v50
.LBB0_790:
	v_exp_f32_e32 v99, v66
	v_exp_f32_e32 v98, v82
	v_exp_f32_e32 v67, v67
	v_exp_f32_e32 v66, v83
	v_exp_f32_e32 v83, v68
	v_exp_f32_e32 v82, v84
	v_exp_f32_e32 v69, v69
	v_exp_f32_e32 v68, v85
	s_waitcnt lgkmcnt(3)
	v_pk_fma_f32 v[84:85], v[46:47], v[98:99], 0 op_sel_hi:[0,1,0]
	v_pk_mul_f32 v[172:173], v[46:47], v[98:99] op_sel_hi:[0,1]
	v_pk_mul_f32 v[176:177], v[46:47], v[66:67] op_sel:[1,0]
	v_pk_fma_f32 v[46:47], v[46:47], v[66:67], v[84:85] op_sel:[1,0,0]
	v_pk_mul_f32 v[180:181], v[48:49], v[82:83] op_sel_hi:[0,1]
	v_pk_fma_f32 v[46:47], v[48:49], v[82:83], v[46:47] op_sel_hi:[0,1,1]
	v_exp_f32_e32 v67, v70
	v_exp_f32_e32 v66, v86
	v_mov_b32_e32 v48, v49
	v_pk_mul_f32 v[184:185], v[48:49], v[68:69] op_sel_hi:[0,1]
	v_pk_fma_f32 v[46:47], v[48:49], v[68:69], v[46:47] op_sel_hi:[0,1,1]
	v_exp_f32_e32 v49, v71
	v_exp_f32_e32 v48, v87
	v_exp_f32_e32 v69, v72
	v_exp_f32_e32 v68, v88
	v_exp_f32_e32 v71, v73
	v_exp_f32_e32 v70, v89
	v_exp_f32_e32 v73, v74
	v_exp_f32_e32 v72, v90
	s_waitcnt lgkmcnt(2)
	v_pk_fma_f32 v[46:47], v[42:43], v[66:67], v[46:47] op_sel_hi:[0,1,1]
	v_pk_mul_f32 v[188:189], v[42:43], v[66:67] op_sel_hi:[0,1]
	v_exp_f32_e32 v75, v75
	v_exp_f32_e32 v74, v91
	v_pk_mul_f32 v[204:205], v[42:43], v[48:49] op_sel:[1,0]
	v_pk_fma_f32 v[42:43], v[42:43], v[48:49], v[46:47] op_sel:[1,0,0]
	v_exp_f32_e32 v83, v76
	v_exp_f32_e32 v82, v92
	v_pk_mul_f32 v[208:209], v[44:45], v[68:69] op_sel_hi:[0,1]
	v_pk_fma_f32 v[42:43], v[44:45], v[68:69], v[42:43] op_sel_hi:[0,1,1]
	v_mov_b32_e32 v44, v45
	v_exp_f32_e32 v77, v77
	v_exp_f32_e32 v76, v93
	v_pk_fma_f32 v[42:43], v[44:45], v[70:71], v[42:43] op_sel_hi:[0,1,1]
	v_exp_f32_e32 v85, v78
	v_exp_f32_e32 v84, v94
	s_waitcnt lgkmcnt(1)
	v_pk_fma_f32 v[42:43], v[38:39], v[72:73], v[42:43] op_sel_hi:[0,1,1]
	v_exp_f32_e32 v79, v79
	v_exp_f32_e32 v78, v95
	v_pk_mul_f32 v[210:211], v[38:39], v[72:73] op_sel_hi:[0,1]
	v_pk_mul_f32 v[190:191], v[38:39], v[74:75] op_sel:[1,0]
	v_pk_fma_f32 v[38:39], v[38:39], v[74:75], v[42:43] op_sel:[1,0,0]
	v_exp_f32_e32 v87, v80
	v_exp_f32_e32 v86, v96
	v_pk_mul_f32 v[192:193], v[40:41], v[82:83] op_sel_hi:[0,1]
	v_pk_fma_f32 v[38:39], v[40:41], v[82:83], v[38:39] op_sel_hi:[0,1,1]
	v_mov_b32_e32 v40, v41
	v_exp_f32_e32 v81, v81
	v_exp_f32_e32 v80, v97
	v_pk_fma_f32 v[38:39], v[40:41], v[76:77], v[38:39] op_sel_hi:[0,1,1]
	s_waitcnt lgkmcnt(0)
	v_pk_fma_f32 v[38:39], v[34:35], v[84:85], v[38:39] op_sel_hi:[0,1,1]
	v_pk_mul_f32 v[186:187], v[34:35], v[84:85] op_sel_hi:[0,1]
	v_pk_mul_f32 v[174:175], v[34:35], v[78:79] op_sel:[1,0]
	v_pk_fma_f32 v[34:35], v[34:35], v[78:79], v[38:39] op_sel:[1,0,0]
	v_pk_mul_f32 v[178:179], v[36:37], v[86:87] op_sel_hi:[0,1]
	v_pk_fma_f32 v[34:35], v[36:37], v[86:87], v[34:35] op_sel_hi:[0,1,1]
	v_mov_b32_e32 v36, v37
	v_pk_fma_f32 v[34:35], v[36:37], v[80:81], v[34:35] op_sel_hi:[0,1,1]
	v_pk_mul_f32 v[206:207], v[44:45], v[70:71] op_sel_hi:[0,1]
	v_pk_mul_f32 v[182:183], v[40:41], v[76:77] op_sel_hi:[0,1]
	v_pk_mul_f32 v[168:169], v[36:37], v[80:81] op_sel_hi:[0,1]
	v_add_f32_e32 v170, v34, v35
	v_mov_b32_e32 v223, v224
	v_mov_b32_e32 v227, v222
